# plus prologue: every other 8-workgroup group builds the small tables before the x conversion
# baseline (speedup 1.0000x reference)
; #define LAS __attribute__((address_space(3)))
; __device__ __forceinline__ unsigned xb_add(unsigned* p, unsigned v) { return __hip_atomic_fetch_add(p, v, __ATOMIC_RELAXED, __HIP_MEMORY_SCOPE_AGENT); }
; __device__ __forceinline__ unsigned xb_xcc_id() { return (unsigned)__builtin_amdgcn_s_getreg((3 << 11) | 20) & 0xFu; }
; #define GPTR(T, p) gptr_<T>(p)
; __device__ __forceinline__ XcdBarrier xcd_barrier_post(unsigned* bar, volatile LAS unsigned* st) {
;     XcdBarrier b; b.bar = bar; b.x = xb_xcc_id(); b.st = st;
;     if (threadIdx.x == 0) (void)xb_add(&bar[XB_XCNT(b.x)], 1u);
;     return b;
; __global__ void __launch_bounds__(NWAVES * 64, 2) hymba_fwd(Args args) {
;     ...
;     const int tid = threadIdx.x, lane = tid & 63, wave = __builtin_amdgcn_readfirstlane(tid >> 6);
;     const int G0 = gridDim.x, bx0 = blockIdx.x;
;     const int G = G0, bx = bx0;
;     const bool FUSED_FINAL = (N_LAUNCHES == 1) && G == (MP / 256) * (DM / 256);
;     unsigned char* ws = GPTR(unsigned char, args.ws);
;     gu32* ctl = (gu32*)(ws + WS_CTL);
;     for (int u = tid; u < (LDS_BYTES - LDSCTL_OFF) / 4; u += NWAVES * 64) ((LAS unsigned*)(lds + LDSCTL_OFF))[u] = 0u;
;     __syncthreads();
;     XcdBarrier bar; bar.bar = (unsigned*)(ctl + CW_BAR); bar.x = 0; bar.st = nullptr;
;     if (N_LAUNCHES == 1) bar = xcd_barrier_post((unsigned*)(ctl + CW_BAR), MISC + 8);
_Z9hymba_fwd4Args:
	s_mov_b32 s100, 0
	s_load_dwordx4 s[4:7], s[0:1], 0x100
	v_writelane_b32 v252, s2, 0
	s_add_u32 s2, s0, 0x120
	s_addc_u32 s3, s1, 0
	v_writelane_b32 v252, s2, 1
	v_lshl_add_u32 v1, v0, 2, 0
	v_add_u32_e32 v1, 0x20000, v1
	v_writelane_b32 v252, s3, 2
	s_load_dword s2, s[0:1], 0x120
	v_mov_b32_e32 v2, 0
	v_readfirstlane_b32 s8, v0
	s_waitcnt lgkmcnt(0)
	v_writelane_b32 v252, s2, 3
	v_writelane_b32 v252, s4, 4
	s_mov_b64 s[2:3], s[6:7]
	ds_write2st64_b32 v1, v2, v2 offset1:8
	ds_write2st64_b32 v1, v2, v2 offset0:16 offset1:24
	v_writelane_b32 v252, s5, 5
	v_writelane_b32 v252, s6, 6
	v_writelane_b32 v252, s7, 7
	v_or_b32_e32 v1, 0x800, v0
	s_mov_b64 s[4:5], -1
	s_and_saveexec_b64 s[6:7], s[4:5]
	v_lshl_add_u32 v3, v1, 2, 0
	v_add_u32_e32 v3, 0x20000, v3
	ds_write_b32 v3, v2
	s_or_b64 exec, exec, s[6:7]
	s_and_saveexec_b64 s[6:7], s[4:5]
	s_add_i32 s4, 0, 0x20000
	v_lshl_add_u32 v1, v1, 2, s4
	v_mov_b32_e32 v2, 0
	ds_write_b32 v1, v2 offset:2048
	s_or_b64 exec, exec, s[6:7]
	v_or_b32_e32 v1, 0xc00, v0
	v_cmp_gt_u32_e64 s[4:5], 7, 6
	v_cmp_gt_u32_e64 s[10:11], 7, 5
	s_and_saveexec_b64 s[6:7], s[10:11]
	v_lshl_add_u32 v2, v1, 2, 0
	v_add_u32_e32 v2, 0x20000, v2
	v_mov_b32_e32 v3, 0
	ds_write_b32 v2, v3
	s_or_b64 exec, exec, s[6:7]
	s_load_dwordx2 s[6:7], s[0:1], 0x110
	s_waitcnt lgkmcnt(0)
	v_writelane_b32 v252, s6, 8
	s_nop 1
	v_writelane_b32 v252, s7, 9
	s_and_saveexec_b64 s[6:7], s[4:5]
	s_add_i32 s4, 0, 0x20000
	v_lshl_add_u32 v1, v1, 2, s4
	v_mov_b32_e32 v2, 0
	ds_write_b32 v1, v2 offset:2048
	s_or_b64 exec, exec, s[6:7]
	s_load_dwordx16 s[12:27], s[0:1], 0x0
	s_add_u32 s2, s2, 0x4000
	s_addc_u32 s3, s3, 0
	s_waitcnt lgkmcnt(0)
	s_barrier
	v_writelane_b32 v252, s12, 10
	v_cmp_eq_u32_e64 s[4:5], 0, v0
	s_nop 0
	v_writelane_b32 v252, s13, 11
	v_writelane_b32 v252, s14, 12
	v_writelane_b32 v252, s15, 13
	v_writelane_b32 v252, s16, 14
	v_writelane_b32 v252, s17, 15
	v_writelane_b32 v252, s18, 16
	v_writelane_b32 v252, s19, 17
	v_writelane_b32 v252, s20, 18
	v_writelane_b32 v252, s21, 19
	v_writelane_b32 v252, s22, 20
	v_writelane_b32 v252, s23, 21
	v_writelane_b32 v252, s24, 22
	v_writelane_b32 v252, s25, 23
	v_writelane_b32 v252, s26, 24
	v_writelane_b32 v252, s27, 25
	s_load_dwordx16 s[12:27], s[0:1], 0x80
	s_waitcnt lgkmcnt(0)
	v_writelane_b32 v252, s12, 26
	s_nop 1
	v_writelane_b32 v252, s13, 27
	v_writelane_b32 v252, s14, 28
	v_writelane_b32 v252, s15, 29
	v_writelane_b32 v252, s16, 30
	v_writelane_b32 v252, s17, 31
	v_writelane_b32 v252, s18, 32
	v_writelane_b32 v252, s19, 33
	v_writelane_b32 v252, s20, 34
	v_writelane_b32 v252, s21, 35
	v_writelane_b32 v252, s22, 36
	v_writelane_b32 v252, s23, 37
	v_writelane_b32 v252, s24, 38
	v_writelane_b32 v252, s25, 39
	v_writelane_b32 v252, s26, 40
	v_writelane_b32 v252, s27, 41
	v_writelane_b32 v252, s2, 42
	s_nop 1
	v_writelane_b32 v252, s3, 43
	s_getreg_b32 s2, hwreg(HW_REG_XCC_ID, 0, 4)
	s_and_b32 s2, s2, 15
	v_writelane_b32 v252, s2, 44
	s_mov_b64 s[2:3], exec
	v_writelane_b32 v252, s4, 45
	s_nop 1
	v_writelane_b32 v252, s5, 46
	s_and_b64 s[4:5], s[2:3], s[4:5]
	s_mov_b64 exec, s[4:5]
	s_cbranch_execz .LBB0_11
	s_mov_b64 s[4:5], exec
	v_mbcnt_lo_u32_b32 v1, s4, 0
	v_mbcnt_hi_u32_b32 v1, s5, v1
	v_cmp_eq_u32_e32 vcc, 0, v1
	s_and_b64 s[6:7], exec, vcc
	s_mov_b64 exec, s[6:7]
	s_cbranch_execz .LBB0_11
	v_readlane_b32 s6, v252, 44
	s_bcnt1_i32_b64 s4, s[4:5]
	s_lshl_b32 s6, s6, 8
	v_mov_b32_e32 v2, s4
	v_readlane_b32 s4, v252, 42
	v_mov_b32_e32 v1, s6
	v_readlane_b32 s5, v252, 43
	s_nop 4
	global_atomic_add v1, v2, s[4:5] offset:1024

; __device__ __forceinline__ void p0_prologue(const Args& args, LAS unsigned char* lds, int tid, int lane, int wave, int bx, int G) {
;     ...
;     {
;         bf16* hb = (bf16*)(ws + WS_HB); float* ssq = (float*)(ws + WS_SSQ0);
;         for (int m0 = gw; m0 < M; m0 += 3 * NGW) {
.LBB0_54:
	v_readlane_b32 s70, v252, 0
	s_nop 3
	s_bitcmp1_b32 s70, 3
	s_cbranch_scc0 .Lp0_A
	s_mov_b32 s71, s8
	s_mov_b32 s74, s12
	s_mov_b32 s75, s13
	s_mov_b32 s76, s16
	s_mov_b32 s77, s17
	s_mov_b32 s78, s26
	s_mov_b32 s79, s27
	v_mov_b32_e32 v100, v3
	v_lshlrev_b32_e32 v50, 2, v1
	s_mov_b32 s100, 1
	s_branch .LBB0_83

; #define GIN(i) GPTR(const float, args.in[i])
; __device__ __forceinline__ void p0_prologue(const Args& args, LAS unsigned char* lds, int tid, int lane, int wave, int bx, int G) {
;     ...
;         }
;     }
;     if (gt < DEPTH * NG * NP) {
;         const int L = gt >> 11, gp = gt & 2047, g = gp >> 6;
;         float* tb = (float*)(ws + WS_TB) + (size_t)L * TB_LAYER;
;         double lr = (double)GIN(I_LRE)[L * 2048 + gp]; lr = lr < -1e-4 ? lr : -1e-4;
.LBB0_83:
	s_cmp_eq_u32 s100, 2
	s_cbranch_scc0 .Lp0_B
	s_mov_b32 s100, 0
	s_mov_b32 s9, s80
	s_mov_b32 s11, s81
	s_mov_b32 s16, s82
	s_mov_b32 s17, s83
	s_mov_b32 s21, s84
	s_mov_b32 s27, s85
	s_mov_b32 s36, s86
	s_mov_b32 s39, s87
	s_mov_b32 s40, s88
	s_mov_b32 s42, s89
	s_mov_b32 s43, s90
	s_mov_b32 s48, s91
	s_branch .Lp0_end

; __device__ __forceinline__ unsigned f2bf(float f) { unsigned u = __builtin_bit_cast(unsigned, f); return (u + 0x7fffu + ((u >> 16) & 1u)) >> 16; }
; __device__ __forceinline__ float bf1(bf16 h) { return __uint_as_float((unsigned)h << 16); }
; #define GIN(i) GPTR(const float, args.in[i])
; __device__ __forceinline__ void p0_prologue(const Args& args, LAS unsigned char* lds, int tid, int lane, int wave, int bx, int G) {
;     ...
;     {
;         bf16* wsm = (bf16*)(ws + WS_WSM); const float* w_s = GIN(I_WS);
;         for (int e = gt; e < DEPTH * NH * CHUNK * CHUNK; e += NGT) { const int s = e & 127, t = (e >> 7) & 127; wsm[e] = (s <= t) ? (bf16)f2bf(w_s[e]) : (bf16)0; }
;         float* wsum = (float*)(ws + WS_WSUM);
;         for (int e = gw; e < DEPTH * NH * CHUNK; e += NGW) { const int t = e & 127;
;             const float a0 = (lane <= t) ? bf1((bf16)f2bf(w_s[(size_t)e * CHUNK + lane])) : 0.f, a1 = (lane + 64 <= t) ? bf1((bf16)f2bf(w_s[(size_t)e * CHUNK + 64 + lane])) : 0.f;
;             const float a = wave_sum(a0 + a1); if (lane == 0) wsum[e] = a; }
;     }
; }
.LBB0_114:
	s_cmp_eq_u32 s100, 1
	s_cbranch_scc0 .Lp0_end
	s_mov_b32 s100, 2
	s_mov_b32 s80, s9
	s_mov_b32 s81, s11
	s_mov_b32 s82, s16
	s_mov_b32 s83, s17
	s_mov_b32 s84, s21
	s_mov_b32 s85, s27
	s_mov_b32 s86, s36
	s_mov_b32 s87, s39
	s_mov_b32 s88, s40
	s_mov_b32 s89, s42
	s_mov_b32 s90, s43
	s_mov_b32 s91, s48
	s_mov_b32 s8, s71
	s_mov_b32 s12, s74
	s_mov_b32 s13, s75
	s_mov_b32 s16, s76
	s_mov_b32 s17, s77
	s_mov_b32 s26, s78
	s_mov_b32 s27, s79
	v_mov_b32_e32 v3, v100
	s_branch .Lp0_A

; #define LAS __attribute__((address_space(3)))
; __global__ void __launch_bounds__(NWAVES * 64, 2) hymba_fwd(Args args) {
;     extern __shared__ __attribute__((aligned(16))) unsigned char lds_raw[];
;     LAS unsigned char* lds = (LAS unsigned char*)lds_raw;
	.amdhsa_kernel _Z9hymba_fwd4Args
		.amdhsa_group_segment_fixed_size 0
		.amdhsa_private_segment_fixed_size 0
		.amdhsa_kernarg_size 544
		.amdhsa_user_sgpr_count 2
		.amdhsa_user_sgpr_dispatch_ptr 0
		.amdhsa_user_sgpr_queue_ptr 0
		.amdhsa_user_sgpr_kernarg_segment_ptr 1
		.amdhsa_user_sgpr_dispatch_id 0
		.amdhsa_user_sgpr_kernarg_preload_length 0
		.amdhsa_user_sgpr_kernarg_preload_offset 0
		.amdhsa_user_sgpr_private_segment_size 0
		.amdhsa_uses_dynamic_stack 0
		.amdhsa_enable_private_segment 0
		.amdhsa_system_sgpr_workgroup_id_x 1
		.amdhsa_system_sgpr_workgroup_id_y 0
		.amdhsa_system_sgpr_workgroup_id_z 0
		.amdhsa_system_sgpr_workgroup_info 0
		.amdhsa_system_vgpr_workitem_id 0
		.amdhsa_next_free_vgpr 256
		.amdhsa_next_free_sgpr 102
		.amdhsa_accum_offset 256
		.amdhsa_reserve_vcc 1
		.amdhsa_float_round_mode_32 0
		.amdhsa_float_round_mode_16_64 0
		.amdhsa_float_denorm_mode_32 3
		.amdhsa_float_denorm_mode_16_64 3
		.amdhsa_dx10_clamp 1
		.amdhsa_ieee_mode 1
		.amdhsa_fp16_overflow 0
		.amdhsa_tg_split 0
		.amdhsa_exception_fp_ieee_invalid_op 0
		.amdhsa_exception_fp_denorm_src 0
		.amdhsa_exception_fp_ieee_div_zero 0
		.amdhsa_exception_fp_ieee_overflow 0
		.amdhsa_exception_fp_ieee_underflow 0
		.amdhsa_exception_fp_ieee_inexact 0
		.amdhsa_exception_int_div_zero 0
	.end_amdhsa_kernel

; __global__ void __launch_bounds__(NWAVES * 64, 2) hymba_fwd(Args args) {
;     extern __shared__ __attribute__((aligned(16))) unsigned char lds_raw[];
.Lfunc_end0:
	.size	_Z9hymba_fwd4Args, .Lfunc_end0-_Z9hymba_fwd4Args
	.set _Z9hymba_fwd4Args.num_vgpr, 256
	.set _Z9hymba_fwd4Args.num_agpr, 0
	.set _Z9hymba_fwd4Args.numbered_sgpr, 102
	.set _Z9hymba_fwd4Args.num_named_barrier, 0
	.set _Z9hymba_fwd4Args.private_seg_size, 0
	.set _Z9hymba_fwd4Args.uses_vcc, 1
	.set _Z9hymba_fwd4Args.uses_flat_scratch, 0
	.set _Z9hymba_fwd4Args.has_dyn_sized_stack, 0
	.set _Z9hymba_fwd4Args.has_recursion, 0
	.set _Z9hymba_fwd4Args.has_indirect_call, 0

; __global__ void __launch_bounds__(NWAVES * 64, 2) hymba_fwd(Args args) {
;     extern __shared__ __attribute__((aligned(16))) unsigned char lds_raw[];
amdhsa.kernels:
  - .agpr_count:     0
    .args:
      - .offset:         0
        .size:           288
        .value_kind:     by_value
      - .offset:         288
        .size:           4
        .value_kind:     hidden_block_count_x
      - .offset:         292
        .size:           4
        .value_kind:     hidden_block_count_y
      - .offset:         296
        .size:           4
        .value_kind:     hidden_block_count_z
      - .offset:         300
        .size:           2
        .value_kind:     hidden_group_size_x
      - .offset:         302
        .size:           2
        .value_kind:     hidden_group_size_y
      - .offset:         304
        .size:           2
        .value_kind:     hidden_group_size_z
      - .offset:         306
        .size:           2
        .value_kind:     hidden_remainder_x
      - .offset:         308
        .size:           2
        .value_kind:     hidden_remainder_y
      - .offset:         310
        .size:           2
        .value_kind:     hidden_remainder_z
      - .offset:         328
        .size:           8
        .value_kind:     hidden_global_offset_x
      - .offset:         336
        .size:           8
        .value_kind:     hidden_global_offset_y
      - .offset:         344
        .size:           8
        .value_kind:     hidden_global_offset_z
      - .offset:         352
        .size:           2
        .value_kind:     hidden_grid_dims
      - .offset:         408
        .size:           4
        .value_kind:     hidden_dynamic_lds_size
    .group_segment_fixed_size: 0
    .kernarg_segment_align: 8
    .kernarg_segment_size: 544
    .language:       OpenCL C
    .language_version:
      - 2
      - 0
    .max_flat_workgroup_size: 512
    .name:           _Z9hymba_fwd4Args
    .private_segment_fixed_size: 0
    .sgpr_count:     108
    .sgpr_spill_count: 429
    .symbol:         _Z9hymba_fwd4Args.kd
    .uniform_work_group_size: 1
    .uses_dynamic_stack: false
    .vgpr_count:     256
    .vgpr_spill_count: 0
    .wavefront_size: 64
